# adds: EpiSwiglu stores lane-permuted with ds_bpermute so adjacent lanes write adjacent 16B chunks of a row (TA-friendlier store shape)
# speedup vs baseline: 1.0029x; 1.0029x over previous
.LBB0_78:
	s_waitcnt lgkmcnt(0)
	v_lshl_or_b32 v192, s2, 7, v173
	v_lshlrev_b32_e32 v192, 1, v192
	v_and_b32_e32 v194, 15, v252
	v_lshrrev_b32_e32 v195, 2, v252
	v_sub_u32_e32 v194, v195, v194
	v_and_b32_e32 v196, 3, v252
	v_lshrrev_b32_e32 v197, 4, v252
	v_lshl_or_b32 v195, v196, 4, v195
	v_lshlrev_b32_e32 v195, 2, v195
	v_sub_u32_e32 v196, v196, v197
	v_lshl_add_u32 v193, v196, 4, v192
	v_mul_f32_e32 v182, v170, v170
	v_mul_f32_e32 v180, 0xbfb8aa3b, v170
	v_rcp_f32_e32 v182, v182
	v_pk_mul_f32 v[122:123], v[126:127], v[122:123]
	v_pk_mul_f32 v[124:125], v[128:129], v[124:125]
	v_pk_mul_f32 v[126:127], v[126:127], v[180:181] op_sel_hi:[1,0]
	v_pk_mul_f32 v[114:115], v[118:119], v[114:115]
	v_pk_mul_f32 v[128:129], v[128:129], v[180:181] op_sel_hi:[1,0]
	v_exp_f32_e32 v126, v126
	v_exp_f32_e32 v127, v127
	v_mul_f32_e32 v186, v171, v171
	v_mul_f32_e32 v184, 0xbfb8aa3b, v171
	v_rcp_f32_e32 v186, v186
	v_pk_mul_f32 v[116:117], v[120:121], v[116:117]
	v_pk_mul_f32 v[118:119], v[118:119], v[180:181] op_sel_hi:[1,0]
	v_exp_f32_e32 v128, v128
	v_exp_f32_e32 v129, v129
	v_pk_fma_f32 v[126:127], v[126:127], v[182:183], v[182:183] op_sel_hi:[1,0,0]
	v_pk_mul_f32 v[106:107], v[110:111], v[106:107]
	v_pk_mul_f32 v[120:121], v[120:121], v[180:181] op_sel_hi:[1,0]
	v_exp_f32_e32 v118, v118
	v_exp_f32_e32 v119, v119
	v_pk_fma_f32 v[128:129], v[128:129], v[182:183], v[182:183] op_sel_hi:[1,0,0]
	v_rcp_f32_e32 v126, v126
	v_rcp_f32_e32 v127, v127
	v_pk_mul_f32 v[108:109], v[112:113], v[108:109]
	v_pk_mul_f32 v[110:111], v[110:111], v[184:185] op_sel_hi:[1,0]
	v_exp_f32_e32 v120, v120
	v_exp_f32_e32 v121, v121
	v_pk_fma_f32 v[118:119], v[118:119], v[182:183], v[182:183] op_sel_hi:[1,0,0]
	v_rcp_f32_e32 v128, v128
	v_rcp_f32_e32 v129, v129
	v_pk_mul_f32 v[122:123], v[122:123], v[126:127]
	v_pk_mul_f32 v[98:99], v[102:103], v[98:99]
	v_pk_mul_f32 v[112:113], v[112:113], v[184:185] op_sel_hi:[1,0]
	v_exp_f32_e32 v110, v110
	v_exp_f32_e32 v111, v111
	v_pk_fma_f32 v[120:121], v[120:121], v[182:183], v[182:183] op_sel_hi:[1,0,0]
	v_rcp_f32_e32 v118, v118
	v_rcp_f32_e32 v119, v119
	v_pk_mul_f32 v[124:125], v[124:125], v[128:129]
	v_mul_f32_e32 v182, v162, v162
	v_mul_f32_e32 v180, 0xbfb8aa3b, v162
	v_rcp_f32_e32 v182, v182
	v_pk_mul_f32 v[100:101], v[104:105], v[100:101]
	v_pk_mul_f32 v[102:103], v[102:103], v[184:185] op_sel_hi:[1,0]
	v_exp_f32_e32 v112, v112
	v_exp_f32_e32 v113, v113
	v_pk_fma_f32 v[110:111], v[110:111], v[186:187], v[186:187] op_sel_hi:[1,0,0]
	v_rcp_f32_e32 v120, v120
	v_rcp_f32_e32 v121, v121
	v_pk_mul_f32 v[114:115], v[114:115], v[118:119]
	v_pk_mul_f32 v[88:89], v[92:93], v[88:89]
	v_pk_mul_f32 v[104:105], v[104:105], v[184:185] op_sel_hi:[1,0]
	v_exp_f32_e32 v102, v102
	v_exp_f32_e32 v103, v103
	v_pk_fma_f32 v[112:113], v[112:113], v[186:187], v[186:187] op_sel_hi:[1,0,0]
	v_rcp_f32_e32 v110, v110
	v_rcp_f32_e32 v111, v111
	v_pk_mul_f32 v[116:117], v[116:117], v[120:121]
	v_pk_mul_f32 v[90:91], v[94:95], v[90:91]
	v_pk_mul_f32 v[92:93], v[92:93], v[180:181] op_sel_hi:[1,0]
	v_exp_f32_e32 v104, v104
	v_exp_f32_e32 v105, v105
	v_pk_fma_f32 v[102:103], v[102:103], v[186:187], v[186:187] op_sel_hi:[1,0,0]
	v_rcp_f32_e32 v112, v112
	v_rcp_f32_e32 v113, v113
	v_pk_mul_f32 v[106:107], v[106:107], v[110:111]
	v_add_u32_e32 v188, v168, v194
	v_mov_b32_e32 v189, 0
	v_cvt_pk_bf16_f32 v126, v122, v123
	v_cvt_pk_bf16_f32 v127, v124, v125
	v_cvt_pk_bf16_f32 v128, v114, v115
	v_cvt_pk_bf16_f32 v129, v116, v117
	v_mul_u32_u24_e32 v188, s65, v188
	ds_bpermute_b32 v126, v195, v126
	ds_bpermute_b32 v127, v195, v127
	ds_bpermute_b32 v128, v195, v128
	ds_bpermute_b32 v129, v195, v129
	v_add_u32_e32 v188, v188, v193
	v_lshl_add_u64 v[188:189], v[188:189], 0, s[8:9]
	v_pk_mul_f32 v[80:81], v[84:85], v[80:81]
	v_pk_mul_f32 v[94:95], v[94:95], v[180:181] op_sel_hi:[1,0]
	v_exp_f32_e32 v92, v92
	v_exp_f32_e32 v93, v93
	v_pk_fma_f32 v[104:105], v[104:105], v[186:187], v[186:187] op_sel_hi:[1,0,0]
	v_rcp_f32_e32 v102, v102
	v_rcp_f32_e32 v103, v103
	v_pk_mul_f32 v[108:109], v[108:109], v[112:113]
	v_mul_f32_e32 v186, v163, v163
	v_mul_f32_e32 v184, 0xbfb8aa3b, v163
	v_rcp_f32_e32 v186, v186
	v_pk_mul_f32 v[82:83], v[86:87], v[82:83]
	v_pk_mul_f32 v[84:85], v[84:85], v[180:181] op_sel_hi:[1,0]
	v_exp_f32_e32 v94, v94
	v_exp_f32_e32 v95, v95
	v_pk_fma_f32 v[92:93], v[92:93], v[182:183], v[182:183] op_sel_hi:[1,0,0]
	v_rcp_f32_e32 v104, v104
	v_rcp_f32_e32 v105, v105
	v_pk_mul_f32 v[98:99], v[98:99], v[102:103]
	v_pk_mul_f32 v[72:73], v[76:77], v[72:73]
	v_pk_mul_f32 v[86:87], v[86:87], v[180:181] op_sel_hi:[1,0]
	v_exp_f32_e32 v84, v84
	v_exp_f32_e32 v85, v85
	v_pk_fma_f32 v[94:95], v[94:95], v[182:183], v[182:183] op_sel_hi:[1,0,0]
	v_rcp_f32_e32 v92, v92
	v_rcp_f32_e32 v93, v93
	v_pk_mul_f32 v[100:101], v[100:101], v[104:105]
	v_pk_mul_f32 v[74:75], v[78:79], v[74:75]
	v_pk_mul_f32 v[76:77], v[76:77], v[184:185] op_sel_hi:[1,0]
	v_exp_f32_e32 v86, v86
	v_exp_f32_e32 v87, v87
	v_pk_fma_f32 v[84:85], v[84:85], v[182:183], v[182:183] op_sel_hi:[1,0,0]
	v_rcp_f32_e32 v94, v94
	v_rcp_f32_e32 v95, v95
	v_pk_mul_f32 v[88:89], v[88:89], v[92:93]
	s_waitcnt lgkmcnt(0)
	global_store_dwordx4 v[188:189], v[126:129], off
	v_add_u32_e32 v190, v164, v194
	v_mov_b32_e32 v191, 0
	v_cvt_pk_bf16_f32 v110, v106, v107
	v_cvt_pk_bf16_f32 v111, v108, v109
	v_cvt_pk_bf16_f32 v112, v98, v99
	v_cvt_pk_bf16_f32 v113, v100, v101
	v_mul_u32_u24_e32 v190, s65, v190
	ds_bpermute_b32 v110, v195, v110
	ds_bpermute_b32 v111, v195, v111
	ds_bpermute_b32 v112, v195, v112
	ds_bpermute_b32 v113, v195, v113
	v_add_u32_e32 v190, v190, v193
	v_lshl_add_u64 v[190:191], v[190:191], 0, s[8:9]
	v_pk_mul_f32 v[64:65], v[68:69], v[64:65]
	v_pk_mul_f32 v[78:79], v[78:79], v[184:185] op_sel_hi:[1,0]
	v_exp_f32_e32 v76, v76
	v_exp_f32_e32 v77, v77
	v_pk_fma_f32 v[86:87], v[86:87], v[182:183], v[182:183] op_sel_hi:[1,0,0]
	v_rcp_f32_e32 v84, v84
	v_rcp_f32_e32 v85, v85
	v_pk_mul_f32 v[90:91], v[90:91], v[94:95]
	v_mul_f32_e32 v182, v158, v158
	v_mul_f32_e32 v180, 0xbfb8aa3b, v158
	v_rcp_f32_e32 v182, v182
	v_pk_mul_f32 v[66:67], v[70:71], v[66:67]
	v_pk_mul_f32 v[68:69], v[68:69], v[184:185] op_sel_hi:[1,0]
	v_exp_f32_e32 v78, v78
	v_exp_f32_e32 v79, v79
	v_pk_fma_f32 v[76:77], v[76:77], v[186:187], v[186:187] op_sel_hi:[1,0,0]
	v_rcp_f32_e32 v86, v86
	v_rcp_f32_e32 v87, v87
	v_pk_mul_f32 v[80:81], v[80:81], v[84:85]
	v_pk_mul_f32 v[56:57], v[60:61], v[56:57]
	v_pk_mul_f32 v[70:71], v[70:71], v[184:185] op_sel_hi:[1,0]
	v_exp_f32_e32 v68, v68
	v_exp_f32_e32 v69, v69
	v_pk_fma_f32 v[78:79], v[78:79], v[186:187], v[186:187] op_sel_hi:[1,0,0]
	v_rcp_f32_e32 v76, v76
	v_rcp_f32_e32 v77, v77
	v_pk_mul_f32 v[82:83], v[82:83], v[86:87]
	v_pk_mul_f32 v[58:59], v[62:63], v[58:59]
	v_pk_mul_f32 v[60:61], v[60:61], v[180:181] op_sel_hi:[1,0]
	v_exp_f32_e32 v70, v70
	v_exp_f32_e32 v71, v71
	v_pk_fma_f32 v[68:69], v[68:69], v[186:187], v[186:187] op_sel_hi:[1,0,0]
	v_rcp_f32_e32 v78, v78
	v_rcp_f32_e32 v79, v79
	v_pk_mul_f32 v[72:73], v[72:73], v[76:77]
	s_waitcnt lgkmcnt(0)
	global_store_dwordx4 v[190:191], v[110:113], off
	v_add_u32_e32 v188, v160, v194
	v_mov_b32_e32 v189, 0
	v_cvt_pk_bf16_f32 v92, v88, v89
	v_cvt_pk_bf16_f32 v93, v90, v91
	v_cvt_pk_bf16_f32 v94, v80, v81
	v_cvt_pk_bf16_f32 v95, v82, v83
	v_mul_u32_u24_e32 v188, s65, v188
	ds_bpermute_b32 v92, v195, v92
	ds_bpermute_b32 v93, v195, v93
	ds_bpermute_b32 v94, v195, v94
	ds_bpermute_b32 v95, v195, v95
	v_add_u32_e32 v188, v188, v193
	v_lshl_add_u64 v[188:189], v[188:189], 0, s[8:9]
	v_pk_mul_f32 v[48:49], v[52:53], v[48:49]
	v_pk_mul_f32 v[62:63], v[62:63], v[180:181] op_sel_hi:[1,0]
	v_exp_f32_e32 v60, v60
	v_exp_f32_e32 v61, v61
	v_pk_fma_f32 v[70:71], v[70:71], v[186:187], v[186:187] op_sel_hi:[1,0,0]
	v_rcp_f32_e32 v68, v68
	v_rcp_f32_e32 v69, v69
	v_pk_mul_f32 v[74:75], v[74:75], v[78:79]
	v_mul_f32_e32 v186, v159, v159
	v_mul_f32_e32 v184, 0xbfb8aa3b, v159
	v_rcp_f32_e32 v186, v186
	v_pk_mul_f32 v[50:51], v[54:55], v[50:51]
	v_pk_mul_f32 v[52:53], v[52:53], v[180:181] op_sel_hi:[1,0]
	v_exp_f32_e32 v62, v62
	v_exp_f32_e32 v63, v63
	v_pk_fma_f32 v[60:61], v[60:61], v[182:183], v[182:183] op_sel_hi:[1,0,0]
	v_rcp_f32_e32 v70, v70
	v_rcp_f32_e32 v71, v71
	v_pk_mul_f32 v[64:65], v[64:65], v[68:69]
	v_pk_mul_f32 v[40:41], v[44:45], v[40:41]
	v_pk_mul_f32 v[54:55], v[54:55], v[180:181] op_sel_hi:[1,0]
	v_exp_f32_e32 v52, v52
	v_exp_f32_e32 v53, v53
	v_pk_fma_f32 v[62:63], v[62:63], v[182:183], v[182:183] op_sel_hi:[1,0,0]
	v_rcp_f32_e32 v60, v60
	v_rcp_f32_e32 v61, v61
	v_pk_mul_f32 v[66:67], v[66:67], v[70:71]
	v_pk_mul_f32 v[42:43], v[46:47], v[42:43]
	v_pk_mul_f32 v[44:45], v[44:45], v[184:185] op_sel_hi:[1,0]
	v_exp_f32_e32 v54, v54
	v_exp_f32_e32 v55, v55
	v_pk_fma_f32 v[52:53], v[52:53], v[182:183], v[182:183] op_sel_hi:[1,0,0]
	v_rcp_f32_e32 v62, v62
	v_rcp_f32_e32 v63, v63
	v_pk_mul_f32 v[56:57], v[56:57], v[60:61]
	s_waitcnt lgkmcnt(0)
	global_store_dwordx4 v[188:189], v[92:95], off
	v_add_u32_e32 v190, v156, v194
	v_mov_b32_e32 v191, 0
	v_cvt_pk_bf16_f32 v76, v72, v73
	v_cvt_pk_bf16_f32 v77, v74, v75
	v_cvt_pk_bf16_f32 v78, v64, v65
	v_cvt_pk_bf16_f32 v79, v66, v67
	v_mul_u32_u24_e32 v190, s65, v190
	ds_bpermute_b32 v76, v195, v76
	ds_bpermute_b32 v77, v195, v77
	ds_bpermute_b32 v78, v195, v78
	ds_bpermute_b32 v79, v195, v79
	v_add_u32_e32 v190, v190, v193
	v_lshl_add_u64 v[190:191], v[190:191], 0, s[8:9]
	v_pk_mul_f32 v[32:33], v[36:37], v[32:33]
	v_pk_mul_f32 v[46:47], v[46:47], v[184:185] op_sel_hi:[1,0]
	v_exp_f32_e32 v44, v44
	v_exp_f32_e32 v45, v45
	v_pk_fma_f32 v[54:55], v[54:55], v[182:183], v[182:183] op_sel_hi:[1,0,0]
	v_rcp_f32_e32 v52, v52
	v_rcp_f32_e32 v53, v53
	v_pk_mul_f32 v[58:59], v[58:59], v[62:63]
	v_mul_f32_e32 v182, v152, v152
	v_mul_f32_e32 v180, 0xbfb8aa3b, v152
	v_rcp_f32_e32 v182, v182
	v_pk_mul_f32 v[34:35], v[38:39], v[34:35]
	v_pk_mul_f32 v[36:37], v[36:37], v[184:185] op_sel_hi:[1,0]
	v_exp_f32_e32 v46, v46
	v_exp_f32_e32 v47, v47
	v_pk_fma_f32 v[44:45], v[44:45], v[186:187], v[186:187] op_sel_hi:[1,0,0]
	v_rcp_f32_e32 v54, v54
	v_rcp_f32_e32 v55, v55
	v_pk_mul_f32 v[48:49], v[48:49], v[52:53]
	v_pk_mul_f32 v[24:25], v[28:29], v[24:25]
	v_pk_mul_f32 v[38:39], v[38:39], v[184:185] op_sel_hi:[1,0]
	v_exp_f32_e32 v36, v36
	v_exp_f32_e32 v37, v37
	v_pk_fma_f32 v[46:47], v[46:47], v[186:187], v[186:187] op_sel_hi:[1,0,0]
	v_rcp_f32_e32 v44, v44
	v_rcp_f32_e32 v45, v45
	v_pk_mul_f32 v[50:51], v[50:51], v[54:55]
	v_pk_mul_f32 v[26:27], v[30:31], v[26:27]
	v_pk_mul_f32 v[28:29], v[28:29], v[180:181] op_sel_hi:[1,0]
	v_exp_f32_e32 v38, v38
	v_exp_f32_e32 v39, v39
	v_pk_fma_f32 v[36:37], v[36:37], v[186:187], v[186:187] op_sel_hi:[1,0,0]
	v_rcp_f32_e32 v46, v46
	v_rcp_f32_e32 v47, v47
	v_pk_mul_f32 v[40:41], v[40:41], v[44:45]
	s_waitcnt lgkmcnt(0)
	global_store_dwordx4 v[190:191], v[76:79], off
	v_add_u32_e32 v188, v154, v194
	v_mov_b32_e32 v189, 0
	v_cvt_pk_bf16_f32 v60, v56, v57
	v_cvt_pk_bf16_f32 v61, v58, v59
	v_cvt_pk_bf16_f32 v62, v48, v49
	v_cvt_pk_bf16_f32 v63, v50, v51
	v_mul_u32_u24_e32 v188, s65, v188
	ds_bpermute_b32 v60, v195, v60
	ds_bpermute_b32 v61, v195, v61
	ds_bpermute_b32 v62, v195, v62
	ds_bpermute_b32 v63, v195, v63
	v_add_u32_e32 v188, v188, v193
	v_lshl_add_u64 v[188:189], v[188:189], 0, s[8:9]
	v_pk_mul_f32 v[16:17], v[20:21], v[16:17]
	v_pk_mul_f32 v[30:31], v[30:31], v[180:181] op_sel_hi:[1,0]
	v_exp_f32_e32 v28, v28
	v_exp_f32_e32 v29, v29
	v_pk_fma_f32 v[38:39], v[38:39], v[186:187], v[186:187] op_sel_hi:[1,0,0]
	v_rcp_f32_e32 v36, v36
	v_rcp_f32_e32 v37, v37
	v_pk_mul_f32 v[42:43], v[42:43], v[46:47]
	v_mul_f32_e32 v186, v153, v153
	v_mul_f32_e32 v184, 0xbfb8aa3b, v153
	v_rcp_f32_e32 v186, v186
	v_pk_mul_f32 v[18:19], v[22:23], v[18:19]
	v_pk_mul_f32 v[20:21], v[20:21], v[180:181] op_sel_hi:[1,0]
	v_exp_f32_e32 v30, v30
	v_exp_f32_e32 v31, v31
	v_pk_fma_f32 v[28:29], v[28:29], v[182:183], v[182:183] op_sel_hi:[1,0,0]
	v_rcp_f32_e32 v38, v38
	v_rcp_f32_e32 v39, v39
	v_pk_mul_f32 v[32:33], v[32:33], v[36:37]
	v_pk_mul_f32 v[8:9], v[12:13], v[8:9]
	v_pk_mul_f32 v[22:23], v[22:23], v[180:181] op_sel_hi:[1,0]
	v_exp_f32_e32 v20, v20
	v_exp_f32_e32 v21, v21
	v_pk_fma_f32 v[30:31], v[30:31], v[182:183], v[182:183] op_sel_hi:[1,0,0]
	v_rcp_f32_e32 v28, v28
	v_rcp_f32_e32 v29, v29
	v_pk_mul_f32 v[34:35], v[34:35], v[38:39]
	v_pk_mul_f32 v[10:11], v[14:15], v[10:11]
	v_pk_mul_f32 v[12:13], v[12:13], v[184:185] op_sel_hi:[1,0]
	v_exp_f32_e32 v22, v22
	v_exp_f32_e32 v23, v23
	v_pk_fma_f32 v[20:21], v[20:21], v[182:183], v[182:183] op_sel_hi:[1,0,0]
	v_rcp_f32_e32 v30, v30
	v_rcp_f32_e32 v31, v31
	v_pk_mul_f32 v[24:25], v[24:25], v[28:29]
	s_waitcnt lgkmcnt(0)
	global_store_dwordx4 v[188:189], v[60:63], off
	v_add_u32_e32 v190, v150, v194
	v_mov_b32_e32 v191, 0
	v_cvt_pk_bf16_f32 v44, v40, v41
	v_cvt_pk_bf16_f32 v45, v42, v43
	v_cvt_pk_bf16_f32 v46, v32, v33
	v_cvt_pk_bf16_f32 v47, v34, v35
	v_mul_u32_u24_e32 v190, s65, v190
	ds_bpermute_b32 v44, v195, v44
	ds_bpermute_b32 v45, v195, v45
	ds_bpermute_b32 v46, v195, v46
	ds_bpermute_b32 v47, v195, v47
	v_add_u32_e32 v190, v190, v193
	v_lshl_add_u64 v[190:191], v[190:191], 0, s[8:9]
	v_pk_mul_f32 v[0:1], v[4:5], v[0:1]
	v_pk_mul_f32 v[14:15], v[14:15], v[184:185] op_sel_hi:[1,0]
	v_exp_f32_e32 v12, v12
	v_exp_f32_e32 v13, v13
	v_pk_fma_f32 v[22:23], v[22:23], v[182:183], v[182:183] op_sel_hi:[1,0,0]
	v_rcp_f32_e32 v20, v20
	v_rcp_f32_e32 v21, v21
	v_pk_mul_f32 v[26:27], v[26:27], v[30:31]
	v_pk_mul_f32 v[2:3], v[6:7], v[2:3]
	v_pk_mul_f32 v[4:5], v[4:5], v[184:185] op_sel_hi:[1,0]
	v_exp_f32_e32 v14, v14
	v_exp_f32_e32 v15, v15
	v_pk_fma_f32 v[12:13], v[12:13], v[186:187], v[186:187] op_sel_hi:[1,0,0]
	v_rcp_f32_e32 v22, v22
	v_rcp_f32_e32 v23, v23
	v_pk_mul_f32 v[16:17], v[16:17], v[20:21]
	v_pk_mul_f32 v[6:7], v[6:7], v[184:185] op_sel_hi:[1,0]
	v_exp_f32_e32 v4, v4
	v_exp_f32_e32 v5, v5
	v_pk_fma_f32 v[14:15], v[14:15], v[186:187], v[186:187] op_sel_hi:[1,0,0]
	v_rcp_f32_e32 v12, v12
	v_rcp_f32_e32 v13, v13
	v_pk_mul_f32 v[18:19], v[18:19], v[22:23]
	v_exp_f32_e32 v6, v6
	v_exp_f32_e32 v7, v7
	v_pk_fma_f32 v[4:5], v[4:5], v[186:187], v[186:187] op_sel_hi:[1,0,0]
	v_rcp_f32_e32 v14, v14
	v_rcp_f32_e32 v15, v15
	v_pk_mul_f32 v[8:9], v[8:9], v[12:13]
	s_waitcnt lgkmcnt(0)
	global_store_dwordx4 v[190:191], v[44:47], off
	v_add_u32_e32 v188, v148, v194
	v_mov_b32_e32 v189, 0
	v_cvt_pk_bf16_f32 v28, v24, v25
	v_cvt_pk_bf16_f32 v29, v26, v27
	v_cvt_pk_bf16_f32 v30, v16, v17
	v_cvt_pk_bf16_f32 v31, v18, v19
	v_mul_u32_u24_e32 v188, s65, v188
	ds_bpermute_b32 v28, v195, v28
	ds_bpermute_b32 v29, v195, v29
	ds_bpermute_b32 v30, v195, v30
	ds_bpermute_b32 v31, v195, v31
	v_add_u32_e32 v188, v188, v193
	v_lshl_add_u64 v[188:189], v[188:189], 0, s[8:9]
	v_pk_fma_f32 v[6:7], v[6:7], v[186:187], v[186:187] op_sel_hi:[1,0,0]
	v_rcp_f32_e32 v4, v4
	v_rcp_f32_e32 v5, v5
	v_pk_mul_f32 v[10:11], v[10:11], v[14:15]
	v_rcp_f32_e32 v6, v6
	v_rcp_f32_e32 v7, v7
	v_pk_mul_f32 v[0:1], v[0:1], v[4:5]
	v_pk_mul_f32 v[2:3], v[2:3], v[6:7]
	s_waitcnt lgkmcnt(0)
	global_store_dwordx4 v[188:189], v[28:31], off
	v_add_u32_e32 v190, v146, v194
	v_mov_b32_e32 v191, 0
	v_cvt_pk_bf16_f32 v12, v8, v9
	v_cvt_pk_bf16_f32 v13, v10, v11
	v_cvt_pk_bf16_f32 v14, v0, v1
	v_cvt_pk_bf16_f32 v15, v2, v3
	v_mul_u32_u24_e32 v190, s65, v190
	ds_bpermute_b32 v12, v195, v12
	ds_bpermute_b32 v13, v195, v13
	ds_bpermute_b32 v14, v195, v14
	ds_bpermute_b32 v15, v195, v15
	v_add_u32_e32 v190, v190, v193
	v_lshl_add_u64 v[190:191], v[190:191], 0, s[8:9]
	s_waitcnt lgkmcnt(0)
	global_store_dwordx4 v[190:191], v[12:15], off
	s_andn2_b64 vcc, exec, s[42:43]
	s_mov_b64 s[20:21], -1
	s_cbranch_vccnz .LBB0_64
	s_andn2_b64 vcc, exec, s[6:7]
	s_cbranch_vccnz .LBB0_63
	s_branch .LBB0_63
